# poll back-off: s_sleep 5 instead of s_sleep 1 in the XCD-local and release poll loops (less atomic pressure on the arrival counter), on stack22
# speedup vs baseline: 1.0015x; 1.0015x over previous
; __device__ __forceinline__ unsigned xb_ld(unsigned* p)              { return __hip_atomic_load(p, __ATOMIC_RELAXED, __HIP_MEMORY_SCOPE_AGENT); }
; #define XB_SPIN(cond, bar) do { unsigned _sp = 0; while (cond) { __builtin_amdgcn_s_sleep(1); \
;     if ((++_sp & 255u) == 0u) { if (xb_ld(&(bar)[XB_TMO])) break; if (_sp > XB_SPIN_CAP) { atomicAdd(&(bar)[XB_TMO], 1u); break; } } } } while (0)
; __device__ __forceinline__ void xcd_barrier(const XcdBarrier& b) {
;     ...
;             else XB_SPIN(xb_ld(&bar[XB_TOPGEN]) == tg, bar);
;             __builtin_amdgcn_fence(__ATOMIC_ACQUIRE, "agent");
;             asm volatile("s_waitcnt vmcnt(0)" ::: "memory");
;         } else {
;             XB_SPIN(xb_ld(&bar[XB_TOPGEN]) == gen, bar);
.Lxb_b1_nspin:
	global_atomic_add v5, v177, v177, s[4:5] offset:128 sc0
	s_waitcnt vmcnt(0)
	v_cmp_ge_u32_e32 vcc, v5, v6
	s_cbranch_vccnz .Lxb_b1_done
	s_sleep 5
	s_add_i32 s100, s100, 1
	s_cmp_lt_u32 s100, 0x40000
	s_cbranch_scc1 .Lxb_b1_nspin

; __device__ __forceinline__ unsigned xb_ld(unsigned* p)              { return __hip_atomic_load(p, __ATOMIC_RELAXED, __HIP_MEMORY_SCOPE_AGENT); }
; #define XB_SPIN(cond, bar) do { unsigned _sp = 0; while (cond) { __builtin_amdgcn_s_sleep(1); \
;     if ((++_sp & 255u) == 0u) { if (xb_ld(&(bar)[XB_TMO])) break; if (_sp > XB_SPIN_CAP) { atomicAdd(&(bar)[XB_TMO], 1u); break; } } } } while (0)
; __device__ __forceinline__ void xcd_barrier(const XcdBarrier& b) {
;     ...
;             else XB_SPIN(xb_ld(&bar[XB_TOPGEN]) == tg, bar);
;             __builtin_amdgcn_fence(__ATOMIC_ACQUIRE, "agent");
;             asm volatile("s_waitcnt vmcnt(0)" ::: "memory");
;         } else {
;             XB_SPIN(xb_ld(&bar[XB_TOPGEN]) == gen, bar);
.Lxb_b2_lspin:
	global_atomic_add v5, v177, v177, s[4:5] sc0
	s_waitcnt vmcnt(0)
	v_cmp_ge_u32_e32 vcc, v5, v2
	s_cbranch_vccnz .Lxb_b2_done
	s_sleep 5
	s_add_i32 s100, s100, 1
	s_cmp_lt_u32 s100, 0x40000
	s_cbranch_scc1 .Lxb_b2_lspin
	s_branch .Lxb_b2_done
